# spin-loop poll interval: s_sleep removed from the two grid-barrier poll loops (back-to-back coherent polls); on top of v82
# speedup vs baseline: 1.0168x; 1.0168x over previous
.LBB0_841:
	s_and_b32 s16, s4, 0xff
	s_mov_b64 s[14:15], -1
	s_cmp_lg_u32 s16, 0
	s_mov_b64 s[40:41], -1
	s_cbranch_scc0 .LBB0_844
	s_and_b64 vcc, exec, s[40:41]
	s_cbranch_vccz .LBB0_840
